# pool-mixer unit epilogue de-serialised (batched z and scale loads, one wait) stacked on the prologue-DMA + gated-GEMM-epilogue variant
# baseline (speedup 1.0000x reference)
; template <int GI> __device__ __forceinline__ void pool_unit_t(const bf16_t* XB, bf16_t* ZB, const bf16_t* WPt, const float* pscale, int R0, int lane) {
;     ...
;     bf16_t* zrow = ZB + (size_t)t * 512 + g * 128; const float* ps = pscale + g * 128;
.LBB0_121:
	v_lshl_add_u64 v[64:65], v[144:145], 1, v[66:67]
	v_lshl_add_u64 v[66:67], v[144:145], 2, s[60:61]
	global_load_dwordx2 v[68:69], v[64:65], off
	global_load_dwordx2 v[70:71], v[64:65], off offset:16
	global_load_dwordx2 v[72:73], v[64:65], off offset:32
	global_load_dwordx2 v[74:75], v[64:65], off offset:48
	global_load_dwordx2 v[76:77], v[64:65], off offset:64
	global_load_dwordx2 v[78:79], v[64:65], off offset:80
	global_load_dwordx2 v[80:81], v[64:65], off offset:96
	global_load_dwordx2 v[82:83], v[64:65], off offset:112
	global_load_dwordx2 v[84:85], v[64:65], off offset:128
	global_load_dwordx2 v[86:87], v[64:65], off offset:144
	global_load_dwordx2 v[88:89], v[64:65], off offset:160
	global_load_dwordx2 v[90:91], v[64:65], off offset:176
	global_load_dwordx2 v[92:93], v[64:65], off offset:192
	global_load_dwordx2 v[94:95], v[64:65], off offset:208
	global_load_dwordx2 v[96:97], v[64:65], off offset:224
	global_load_dwordx2 v[98:99], v[64:65], off offset:240
	global_load_dwordx4 v[164:167], v[66:67], off
	global_load_dwordx4 v[168:171], v[66:67], off offset:32
	global_load_dwordx4 v[172:175], v[66:67], off offset:64
	global_load_dwordx4 v[176:179], v[66:67], off offset:96
	global_load_dwordx4 v[180:183], v[66:67], off offset:128
	global_load_dwordx4 v[184:187], v[66:67], off offset:160
	global_load_dwordx4 v[188:191], v[66:67], off offset:192
	global_load_dwordx4 v[192:195], v[66:67], off offset:224
	global_load_dwordx4 v[196:199], v[66:67], off offset:256
	global_load_dwordx4 v[200:203], v[66:67], off offset:288
	global_load_dwordx4 v[204:207], v[66:67], off offset:320
	global_load_dwordx4 v[208:211], v[66:67], off offset:352
	global_load_dwordx4 v[212:215], v[66:67], off offset:384
	global_load_dwordx4 v[216:219], v[66:67], off offset:416
	global_load_dwordx4 v[220:223], v[66:67], off offset:448
	global_load_dwordx4 v[224:227], v[66:67], off offset:480
	s_mov_b64 s[42:43], 0
	s_mov_b64 s[64:65], 0x1000
	s_waitcnt vmcnt(0) lgkmcnt(0)
; template <int GI> __device__ __forceinline__ void pool_unit_t(const bf16_t* XB, bf16_t* ZB, const bf16_t* WPt, const float* pscale, int R0, int lane) {
;     ...
;     POOL_OUT(acc0, 0); POOL_OUT(acc1, 1); POOL_OUT(acc2, 2); POOL_OUT(acc3, 3);
	v_pk_mul_f32 v[48:49], v[48:49], v[164:165]
	v_pk_mul_f32 v[50:51], v[50:51], v[166:167]
	v_lshlrev_b32_e32 v100, 16, v68
	v_and_b32_e32 v101, 0xffff0000, v68
	v_lshlrev_b32_e32 v102, 16, v69
	v_and_b32_e32 v103, 0xffff0000, v69
	v_pk_mul_f32 v[48:49], v[48:49], v[100:101]
	v_pk_mul_f32 v[50:51], v[50:51], v[102:103]
	v_cvt_pk_bf16_f32 v48, v48, v49
	v_cvt_pk_bf16_f32 v49, v50, v51
	global_store_dwordx2 v[64:65], v[48:49], off
	v_pk_mul_f32 v[52:53], v[52:53], v[168:169]
	v_pk_mul_f32 v[54:55], v[54:55], v[170:171]
	v_lshlrev_b32_e32 v100, 16, v70
	v_and_b32_e32 v101, 0xffff0000, v70
	v_lshlrev_b32_e32 v102, 16, v71
	v_and_b32_e32 v103, 0xffff0000, v71
	v_pk_mul_f32 v[52:53], v[52:53], v[100:101]
	v_pk_mul_f32 v[54:55], v[54:55], v[102:103]
	v_cvt_pk_bf16_f32 v52, v52, v53
	v_cvt_pk_bf16_f32 v53, v54, v55
	global_store_dwordx2 v[64:65], v[52:53], off offset:16
	v_pk_mul_f32 v[56:57], v[56:57], v[172:173]
	v_pk_mul_f32 v[58:59], v[58:59], v[174:175]
	v_lshlrev_b32_e32 v100, 16, v72
	v_and_b32_e32 v101, 0xffff0000, v72
	v_lshlrev_b32_e32 v102, 16, v73
	v_and_b32_e32 v103, 0xffff0000, v73
	v_pk_mul_f32 v[56:57], v[56:57], v[100:101]
	v_pk_mul_f32 v[58:59], v[58:59], v[102:103]
	v_cvt_pk_bf16_f32 v56, v56, v57
	v_cvt_pk_bf16_f32 v57, v58, v59
	global_store_dwordx2 v[64:65], v[56:57], off offset:32
	v_pk_mul_f32 v[60:61], v[60:61], v[176:177]
	v_pk_mul_f32 v[62:63], v[62:63], v[178:179]
	v_lshlrev_b32_e32 v100, 16, v74
	v_and_b32_e32 v101, 0xffff0000, v74
	v_lshlrev_b32_e32 v102, 16, v75
	v_and_b32_e32 v103, 0xffff0000, v75
	v_pk_mul_f32 v[60:61], v[60:61], v[100:101]
	v_pk_mul_f32 v[62:63], v[62:63], v[102:103]
	v_cvt_pk_bf16_f32 v60, v60, v61
	v_cvt_pk_bf16_f32 v61, v62, v63
	global_store_dwordx2 v[64:65], v[60:61], off offset:48
	v_pk_mul_f32 v[32:33], v[32:33], v[180:181]
	v_pk_mul_f32 v[34:35], v[34:35], v[182:183]
	v_lshlrev_b32_e32 v100, 16, v76
	v_and_b32_e32 v101, 0xffff0000, v76
	v_lshlrev_b32_e32 v102, 16, v77
	v_and_b32_e32 v103, 0xffff0000, v77
	v_pk_mul_f32 v[32:33], v[32:33], v[100:101]
	v_pk_mul_f32 v[34:35], v[34:35], v[102:103]
	v_cvt_pk_bf16_f32 v32, v32, v33
	v_cvt_pk_bf16_f32 v33, v34, v35
	global_store_dwordx2 v[64:65], v[32:33], off offset:64
	v_pk_mul_f32 v[36:37], v[36:37], v[184:185]
	v_pk_mul_f32 v[38:39], v[38:39], v[186:187]
	v_lshlrev_b32_e32 v100, 16, v78
	v_and_b32_e32 v101, 0xffff0000, v78
	v_lshlrev_b32_e32 v102, 16, v79
	v_and_b32_e32 v103, 0xffff0000, v79
	v_pk_mul_f32 v[36:37], v[36:37], v[100:101]
	v_pk_mul_f32 v[38:39], v[38:39], v[102:103]
	v_cvt_pk_bf16_f32 v36, v36, v37
	v_cvt_pk_bf16_f32 v37, v38, v39
	global_store_dwordx2 v[64:65], v[36:37], off offset:80
	v_pk_mul_f32 v[40:41], v[40:41], v[188:189]
	v_pk_mul_f32 v[42:43], v[42:43], v[190:191]
	v_lshlrev_b32_e32 v100, 16, v80
	v_and_b32_e32 v101, 0xffff0000, v80
	v_lshlrev_b32_e32 v102, 16, v81
	v_and_b32_e32 v103, 0xffff0000, v81
	v_pk_mul_f32 v[40:41], v[40:41], v[100:101]
	v_pk_mul_f32 v[42:43], v[42:43], v[102:103]
	v_cvt_pk_bf16_f32 v40, v40, v41
	v_cvt_pk_bf16_f32 v41, v42, v43
	global_store_dwordx2 v[64:65], v[40:41], off offset:96
	v_pk_mul_f32 v[44:45], v[44:45], v[192:193]
	v_pk_mul_f32 v[46:47], v[46:47], v[194:195]
	v_lshlrev_b32_e32 v100, 16, v82
	v_and_b32_e32 v101, 0xffff0000, v82
	v_lshlrev_b32_e32 v102, 16, v83
	v_and_b32_e32 v103, 0xffff0000, v83
	v_pk_mul_f32 v[44:45], v[44:45], v[100:101]
	v_pk_mul_f32 v[46:47], v[46:47], v[102:103]
	v_cvt_pk_bf16_f32 v44, v44, v45
	v_cvt_pk_bf16_f32 v45, v46, v47
	global_store_dwordx2 v[64:65], v[44:45], off offset:112
	v_pk_mul_f32 v[16:17], v[16:17], v[196:197]
	v_pk_mul_f32 v[18:19], v[18:19], v[198:199]
	v_lshlrev_b32_e32 v100, 16, v84
	v_and_b32_e32 v101, 0xffff0000, v84
	v_lshlrev_b32_e32 v102, 16, v85
	v_and_b32_e32 v103, 0xffff0000, v85
	v_pk_mul_f32 v[16:17], v[16:17], v[100:101]
	v_pk_mul_f32 v[18:19], v[18:19], v[102:103]
	v_cvt_pk_bf16_f32 v16, v16, v17
	v_cvt_pk_bf16_f32 v17, v18, v19
	global_store_dwordx2 v[64:65], v[16:17], off offset:128
	v_pk_mul_f32 v[20:21], v[20:21], v[200:201]
	v_pk_mul_f32 v[22:23], v[22:23], v[202:203]
	v_lshlrev_b32_e32 v100, 16, v86
	v_and_b32_e32 v101, 0xffff0000, v86
	v_lshlrev_b32_e32 v102, 16, v87
	v_and_b32_e32 v103, 0xffff0000, v87
	v_pk_mul_f32 v[20:21], v[20:21], v[100:101]
	v_pk_mul_f32 v[22:23], v[22:23], v[102:103]
	v_cvt_pk_bf16_f32 v20, v20, v21
	v_cvt_pk_bf16_f32 v21, v22, v23
	global_store_dwordx2 v[64:65], v[20:21], off offset:144
	v_pk_mul_f32 v[24:25], v[24:25], v[204:205]
	v_pk_mul_f32 v[26:27], v[26:27], v[206:207]
	v_lshlrev_b32_e32 v100, 16, v88
	v_and_b32_e32 v101, 0xffff0000, v88
	v_lshlrev_b32_e32 v102, 16, v89
	v_and_b32_e32 v103, 0xffff0000, v89
	v_pk_mul_f32 v[24:25], v[24:25], v[100:101]
	v_pk_mul_f32 v[26:27], v[26:27], v[102:103]
	v_cvt_pk_bf16_f32 v24, v24, v25
	v_cvt_pk_bf16_f32 v25, v26, v27
	global_store_dwordx2 v[64:65], v[24:25], off offset:160
	v_pk_mul_f32 v[28:29], v[28:29], v[208:209]
	v_pk_mul_f32 v[30:31], v[30:31], v[210:211]
	v_lshlrev_b32_e32 v100, 16, v90
	v_and_b32_e32 v101, 0xffff0000, v90
	v_lshlrev_b32_e32 v102, 16, v91
	v_and_b32_e32 v103, 0xffff0000, v91
	v_pk_mul_f32 v[28:29], v[28:29], v[100:101]
	v_pk_mul_f32 v[30:31], v[30:31], v[102:103]
	v_cvt_pk_bf16_f32 v28, v28, v29
	v_cvt_pk_bf16_f32 v29, v30, v31
	global_store_dwordx2 v[64:65], v[28:29], off offset:176
	v_pk_mul_f32 v[0:1], v[0:1], v[212:213]
	v_pk_mul_f32 v[2:3], v[2:3], v[214:215]
	v_lshlrev_b32_e32 v100, 16, v92
	v_and_b32_e32 v101, 0xffff0000, v92
	v_lshlrev_b32_e32 v102, 16, v93
	v_and_b32_e32 v103, 0xffff0000, v93
	v_pk_mul_f32 v[0:1], v[0:1], v[100:101]
	v_pk_mul_f32 v[2:3], v[2:3], v[102:103]
	v_cvt_pk_bf16_f32 v0, v0, v1
	v_cvt_pk_bf16_f32 v1, v2, v3
	global_store_dwordx2 v[64:65], v[0:1], off offset:192
	v_pk_mul_f32 v[4:5], v[4:5], v[216:217]
	v_pk_mul_f32 v[6:7], v[6:7], v[218:219]
	v_lshlrev_b32_e32 v100, 16, v94
	v_and_b32_e32 v101, 0xffff0000, v94
	v_lshlrev_b32_e32 v102, 16, v95
	v_and_b32_e32 v103, 0xffff0000, v95
	v_pk_mul_f32 v[4:5], v[4:5], v[100:101]
	v_pk_mul_f32 v[6:7], v[6:7], v[102:103]
	v_cvt_pk_bf16_f32 v4, v4, v5
	v_cvt_pk_bf16_f32 v5, v6, v7
	global_store_dwordx2 v[64:65], v[4:5], off offset:208
	v_pk_mul_f32 v[8:9], v[8:9], v[220:221]
	v_pk_mul_f32 v[10:11], v[10:11], v[222:223]
	v_lshlrev_b32_e32 v100, 16, v96
	v_and_b32_e32 v101, 0xffff0000, v96
	v_lshlrev_b32_e32 v102, 16, v97
	v_and_b32_e32 v103, 0xffff0000, v97
	v_pk_mul_f32 v[8:9], v[8:9], v[100:101]
	v_pk_mul_f32 v[10:11], v[10:11], v[102:103]
	v_cvt_pk_bf16_f32 v8, v8, v9
	v_cvt_pk_bf16_f32 v9, v10, v11
	global_store_dwordx2 v[64:65], v[8:9], off offset:224
	v_pk_mul_f32 v[12:13], v[12:13], v[224:225]
	v_pk_mul_f32 v[14:15], v[14:15], v[226:227]
	v_lshlrev_b32_e32 v100, 16, v98
	v_and_b32_e32 v101, 0xffff0000, v98
	v_lshlrev_b32_e32 v102, 16, v99
	v_and_b32_e32 v103, 0xffff0000, v99
	v_pk_mul_f32 v[12:13], v[12:13], v[100:101]
	v_pk_mul_f32 v[14:15], v[14:15], v[102:103]
	v_cvt_pk_bf16_f32 v12, v12, v13
	v_cvt_pk_bf16_f32 v13, v14, v15
	global_store_dwordx2 v[64:65], v[12:13], off offset:240
